# in-proj gate quantise path: sigmoid mul/add/scale packed into v_pk_mul/v_pk_add f32 in place (same f32 math, fewer VALU)
# speedup vs baseline: 1.0132x; 1.0072x over previous
.LBB0_701:
	v_lshl_add_u32 v142, s54, 8, v174
	v_ashrrev_i32_e32 v143, 31, v142
	v_lshl_add_u64 v[140:141], v[142:143], 3, s[2:3]
	global_load_dwordx2 v[158:159], v[140:141], off
	global_load_dwordx2 v[156:157], v[140:141], off offset:128
	global_load_dwordx2 v[154:155], v[140:141], off offset:256
	global_load_dwordx2 v[152:153], v[140:141], off offset:384
	global_load_dwordx2 v[150:151], v[140:141], off offset:1024
	global_load_dwordx2 v[148:149], v[140:141], off offset:1152
	global_load_dwordx2 v[146:147], v[140:141], off offset:1280
	global_load_dwordx2 v[144:145], v[140:141], off offset:1408
	s_cmp_gt_i32 s42, 13
	s_cselect_b64 s[0:1], -1, 0
	s_cmp_lt_i32 s42, 14
	s_cselect_b64 s[6:7], -1, 0
	s_and_b64 vcc, s[6:7], exec
	s_cselect_b32 s6, 0, -14
	s_movk_i32 s7, 0xe00
	s_mov_b32 s34, 0x800000
	s_cselect_b32 s25, s18, s31
	s_cselect_b32 s28, s17, s30
	s_cselect_b32 s24, s7, 0xc00
	s_add_i32 s6, s6, s42
	v_lshl_or_b32 v140, s6, 8, v176
	v_ashrrev_i32_e32 v141, 31, v140
	s_mov_b64 s[6:7], -1
	s_waitcnt vmcnt(0)
	v_ffbh_u32_e32 v143, v159
	v_min_u32_e32 v143, 32, v143
	v_lshlrev_b64 v[158:159], v143, v[158:159]
	v_min_u32_e32 v158, 1, v158
	v_or_b32_e32 v158, v159, v158
	v_cvt_f32_u32_e32 v158, v158
	v_sub_u32_e32 v143, 32, v143
	v_ldexp_f32 v143, v158, v143
	v_mul_f32_e32 v143, 0x33800000, v143
	v_fmamk_f32 v143, v143, 0x3a800000, v210
	s_nop 0
	v_rsq_f32_e32 v143, v143
	s_nop 0
	s_nop 0
	v_mov_b32_e32 v158, v143
	v_pk_mul_f32 v[128:129], v[128:129], v[158:159] op_sel_hi:[1,0]
	v_pk_mul_f32 v[170:171], v[126:127], v[158:159] op_sel_hi:[1,0]
	v_pk_mul_f32 v[124:125], v[124:125], v[158:159] op_sel_hi:[1,0]
	v_pk_mul_f32 v[126:127], v[122:123], v[158:159] op_sel_hi:[1,0]
	s_cbranch_vccnz .LBB0_703
	s_mov_b32 s98, 0xbfb8aa3b
	s_mov_b32 s32, 0x437f0000
	v_pk_mul_f32 v[170:171], v[170:171], s[98:99] op_sel_hi:[1,0]
	v_pk_mul_f32 v[128:129], v[128:129], s[98:99] op_sel_hi:[1,0]
	v_pk_mul_f32 v[126:127], v[126:127], s[98:99] op_sel_hi:[1,0]
	v_pk_mul_f32 v[124:125], v[124:125], s[98:99] op_sel_hi:[1,0]
	v_exp_f32_e32 v170, v170
	v_exp_f32_e32 v171, v171
	v_exp_f32_e32 v128, v128
	v_exp_f32_e32 v129, v129
	v_exp_f32_e32 v126, v126
	v_exp_f32_e32 v127, v127
	v_exp_f32_e32 v124, v124
	v_exp_f32_e32 v125, v125
	v_pk_add_f32 v[170:171], v[170:171], 1.0 op_sel_hi:[1,0]
	v_pk_add_f32 v[128:129], v[128:129], 1.0 op_sel_hi:[1,0]
	v_pk_add_f32 v[126:127], v[126:127], 1.0 op_sel_hi:[1,0]
	v_pk_add_f32 v[124:125], v[124:125], 1.0 op_sel_hi:[1,0]
	v_rcp_f32_e32 v170, v170
	v_rcp_f32_e32 v171, v171
	v_rcp_f32_e32 v128, v128
	v_rcp_f32_e32 v129, v129
	v_rcp_f32_e32 v126, v126
	v_rcp_f32_e32 v127, v127
	v_rcp_f32_e32 v124, v124
	v_rcp_f32_e32 v125, v125
	v_pk_mul_f32 v[170:171], v[170:171], s[32:33] op_sel_hi:[1,0]
	v_pk_mul_f32 v[128:129], v[128:129], s[32:33] op_sel_hi:[1,0]
	v_pk_mul_f32 v[126:127], v[126:127], s[32:33] op_sel_hi:[1,0]
	v_pk_mul_f32 v[124:125], v[124:125], s[32:33] op_sel_hi:[1,0]
	v_max_f32_e32 v170, 1.0, v170
	v_max_f32_e32 v171, 1.0, v171
	v_max_f32_e32 v128, 1.0, v128
	v_max_f32_e32 v129, 1.0, v129
	v_max_f32_e32 v126, 1.0, v126
	v_max_f32_e32 v127, 1.0, v127
	v_max_f32_e32 v124, 1.0, v124
	v_max_f32_e32 v125, 1.0, v125
	v_rndne_f32_e32 v170, v170
	v_rndne_f32_e32 v171, v171
	v_rndne_f32_e32 v128, v128
	v_rndne_f32_e32 v129, v129
	v_rndne_f32_e32 v126, v126
	v_rndne_f32_e32 v127, v127
	v_rndne_f32_e32 v124, v124
	v_rndne_f32_e32 v125, v125
	v_cvt_pk_u8_f32 v122, v170, 0, 0
	v_cvt_pk_u8_f32 v122, v171, 1, v122
	v_cvt_pk_u8_f32 v123, v126, 0, 0
	v_cvt_pk_u8_f32 v123, v127, 1, v123
	v_cvt_pk_u8_f32 v122, v128, 2, v122
	v_cvt_pk_u8_f32 v122, v129, 3, v122
	v_cvt_pk_u8_f32 v123, v124, 2, v123
	v_cvt_pk_u8_f32 v123, v125, 3, v123
	v_mov_b64_e32 v[172:173], s[30:31]
	v_mad_i64_i32 v[172:173], s[6:7], v142, s55, v[172:173]
	v_lshl_add_u64 v[172:173], v[172:173], 0, v[140:141]
	s_mov_b64 s[6:7], 0
	v_mov_b32_e32 v246, v122
	v_mov_b32_e32 v247, v123

.LBB0_705:
	v_mov_b32_e32 v124, v158
	v_mov_b32_e32 v125, v158
	v_mov_b32_e32 v159, v158
	v_pk_mul_f32 v[120:121], v[120:121], v[124:125]
	v_pk_mul_f32 v[116:117], v[116:117], v[124:125]
	v_cndmask_b32_e64 v124, 0, 1, s[0:1]
	v_pk_mul_f32 v[118:119], v[118:119], v[158:159]
	v_pk_mul_f32 v[114:115], v[114:115], v[158:159]
	v_cmp_ne_u32_e64 s[42:43], 1, v124
	s_andn2_b64 vcc, exec, s[0:1]
	s_mov_b64 s[0:1], -1
	s_cbranch_vccnz .LBB0_707
	s_mov_b32 s98, 0xbfb8aa3b
	s_mov_b32 s32, 0x437f0000
	v_pk_mul_f32 v[118:119], v[118:119], s[98:99] op_sel_hi:[1,0]
	v_pk_mul_f32 v[120:121], v[120:121], s[98:99] op_sel_hi:[1,0]
	v_pk_mul_f32 v[114:115], v[114:115], s[98:99] op_sel_hi:[1,0]
	v_pk_mul_f32 v[116:117], v[116:117], s[98:99] op_sel_hi:[1,0]
	v_exp_f32_e32 v118, v118
	v_exp_f32_e32 v119, v119
	v_exp_f32_e32 v120, v120
	v_exp_f32_e32 v121, v121
	v_exp_f32_e32 v114, v114
	v_exp_f32_e32 v115, v115
	v_exp_f32_e32 v116, v116
	v_exp_f32_e32 v117, v117
	v_pk_add_f32 v[118:119], v[118:119], 1.0 op_sel_hi:[1,0]
	v_pk_add_f32 v[120:121], v[120:121], 1.0 op_sel_hi:[1,0]
	v_pk_add_f32 v[114:115], v[114:115], 1.0 op_sel_hi:[1,0]
	v_pk_add_f32 v[116:117], v[116:117], 1.0 op_sel_hi:[1,0]
	v_rcp_f32_e32 v118, v118
	v_rcp_f32_e32 v119, v119
	v_rcp_f32_e32 v120, v120
	v_rcp_f32_e32 v121, v121
	v_rcp_f32_e32 v114, v114
	v_rcp_f32_e32 v115, v115
	v_rcp_f32_e32 v116, v116
	v_rcp_f32_e32 v117, v117
	v_pk_mul_f32 v[118:119], v[118:119], s[32:33] op_sel_hi:[1,0]
	v_pk_mul_f32 v[120:121], v[120:121], s[32:33] op_sel_hi:[1,0]
	v_pk_mul_f32 v[114:115], v[114:115], s[32:33] op_sel_hi:[1,0]
	v_pk_mul_f32 v[116:117], v[116:117], s[32:33] op_sel_hi:[1,0]
	v_max_f32_e32 v118, 1.0, v118
	v_max_f32_e32 v119, 1.0, v119
	v_max_f32_e32 v120, 1.0, v120
	v_max_f32_e32 v121, 1.0, v121
	v_max_f32_e32 v114, 1.0, v114
	v_max_f32_e32 v115, 1.0, v115
	v_max_f32_e32 v116, 1.0, v116
	v_max_f32_e32 v117, 1.0, v117
	v_rndne_f32_e32 v118, v118
	v_rndne_f32_e32 v119, v119
	v_rndne_f32_e32 v120, v120
	v_rndne_f32_e32 v121, v121
	v_rndne_f32_e32 v114, v114
	v_rndne_f32_e32 v115, v115
	v_rndne_f32_e32 v116, v116
	v_rndne_f32_e32 v117, v117
	v_cvt_pk_u8_f32 v124, v118, 0, 0
	v_cvt_pk_u8_f32 v124, v119, 1, v124
	v_cvt_pk_u8_f32 v125, v114, 0, 0
	v_cvt_pk_u8_f32 v125, v115, 1, v125
	v_cvt_pk_u8_f32 v124, v120, 2, v124
	v_cvt_pk_u8_f32 v124, v121, 3, v124
	v_cvt_pk_u8_f32 v125, v116, 2, v125
	v_cvt_pk_u8_f32 v125, v117, 3, v125
	v_mov_b64_e32 v[126:127], s[30:31]
	v_mad_i64_i32 v[126:127], s[0:1], v142, s55, v[126:127]
	v_lshl_add_u64 v[126:127], v[126:127], 0, v[140:141]
	s_mov_b64 s[0:1], 0
	v_mov_b32_e32 v244, v124
	v_mov_b32_e32 v245, v125
	v_mov_b32_e32 v250, v176
	v_mov_b32_e32 v251, 0
	v_lshl_add_u64 v[126:127], v[126:127], 0, v[250:251]
	global_store_dwordx4 v[126:127], v[244:247], off

.LBB0_709:
	v_ffbh_u32_e32 v114, v157
	v_min_u32_e32 v116, 32, v114
	v_lshlrev_b64 v[114:115], v116, v[156:157]
	v_min_u32_e32 v114, 1, v114
	v_or_b32_e32 v114, v115, v114
	v_cvt_f32_u32_e32 v114, v114
	v_sub_u32_e32 v115, 32, v116
	v_or_b32_e32 v118, 16, v142
	s_mov_b64 s[0:1], -1
	v_ldexp_f32 v114, v114, v115
	v_mul_f32_e32 v114, 0x33800000, v114
	v_fmamk_f32 v114, v114, 0x3a800000, v210
	s_nop 1
	v_rsq_f32_e32 v114, v114
	s_nop 0
	s_nop 0
	v_pk_mul_f32 v[112:113], v[112:113], v[114:115] op_sel_hi:[1,0]
	v_pk_mul_f32 v[116:117], v[110:111], v[114:115] op_sel_hi:[1,0]
	v_pk_mul_f32 v[108:109], v[108:109], v[114:115] op_sel_hi:[1,0]
	v_pk_mul_f32 v[110:111], v[106:107], v[114:115] op_sel_hi:[1,0]
	s_and_b64 vcc, exec, s[42:43]
	s_cbranch_vccnz .LBB0_711
	s_mov_b32 s98, 0xbfb8aa3b
	s_mov_b32 s32, 0x437f0000
	v_pk_mul_f32 v[116:117], v[116:117], s[98:99] op_sel_hi:[1,0]
	v_pk_mul_f32 v[112:113], v[112:113], s[98:99] op_sel_hi:[1,0]
	v_pk_mul_f32 v[110:111], v[110:111], s[98:99] op_sel_hi:[1,0]
	v_pk_mul_f32 v[108:109], v[108:109], s[98:99] op_sel_hi:[1,0]
	v_exp_f32_e32 v116, v116
	v_exp_f32_e32 v117, v117
	v_exp_f32_e32 v112, v112
	v_exp_f32_e32 v113, v113
	v_exp_f32_e32 v110, v110
	v_exp_f32_e32 v111, v111
	v_exp_f32_e32 v108, v108
	v_exp_f32_e32 v109, v109
	v_pk_add_f32 v[116:117], v[116:117], 1.0 op_sel_hi:[1,0]
	v_pk_add_f32 v[112:113], v[112:113], 1.0 op_sel_hi:[1,0]
	v_pk_add_f32 v[110:111], v[110:111], 1.0 op_sel_hi:[1,0]
	v_pk_add_f32 v[108:109], v[108:109], 1.0 op_sel_hi:[1,0]
	v_rcp_f32_e32 v116, v116
	v_rcp_f32_e32 v117, v117
	v_rcp_f32_e32 v112, v112
	v_rcp_f32_e32 v113, v113
	v_rcp_f32_e32 v110, v110
	v_rcp_f32_e32 v111, v111
	v_rcp_f32_e32 v108, v108
	v_rcp_f32_e32 v109, v109
	v_pk_mul_f32 v[116:117], v[116:117], s[32:33] op_sel_hi:[1,0]
	v_pk_mul_f32 v[112:113], v[112:113], s[32:33] op_sel_hi:[1,0]
	v_pk_mul_f32 v[110:111], v[110:111], s[32:33] op_sel_hi:[1,0]
	v_pk_mul_f32 v[108:109], v[108:109], s[32:33] op_sel_hi:[1,0]
	v_max_f32_e32 v116, 1.0, v116
	v_max_f32_e32 v117, 1.0, v117
	v_max_f32_e32 v112, 1.0, v112
	v_max_f32_e32 v113, 1.0, v113
	v_max_f32_e32 v110, 1.0, v110
	v_max_f32_e32 v111, 1.0, v111
	v_max_f32_e32 v108, 1.0, v108
	v_max_f32_e32 v109, 1.0, v109
	v_rndne_f32_e32 v116, v116
	v_rndne_f32_e32 v117, v117
	v_rndne_f32_e32 v112, v112
	v_rndne_f32_e32 v113, v113
	v_rndne_f32_e32 v110, v110
	v_rndne_f32_e32 v111, v111
	v_rndne_f32_e32 v108, v108
	v_rndne_f32_e32 v109, v109
	v_cvt_pk_u8_f32 v106, v116, 0, 0
	v_cvt_pk_u8_f32 v106, v117, 1, v106
	v_cvt_pk_u8_f32 v107, v110, 0, 0
	v_cvt_pk_u8_f32 v107, v111, 1, v107
	v_cvt_pk_u8_f32 v106, v112, 2, v106
	v_cvt_pk_u8_f32 v106, v113, 3, v106
	v_cvt_pk_u8_f32 v107, v108, 2, v107
	v_cvt_pk_u8_f32 v107, v109, 3, v107
	v_mov_b64_e32 v[120:121], s[30:31]
	v_mad_i64_i32 v[120:121], s[0:1], v118, s55, v[120:121]
	v_lshl_add_u64 v[120:121], v[120:121], 0, v[140:141]
	s_mov_b64 s[0:1], 0
	v_mov_b32_e32 v246, v106
	v_mov_b32_e32 v247, v107

.LBB0_713:
	v_mov_b32_e32 v115, v114
	v_mov_b32_e32 v108, v114
	v_mov_b32_e32 v109, v114
	v_pk_mul_f32 v[104:105], v[104:105], v[108:109]
	v_pk_mul_f32 v[102:103], v[102:103], v[114:115]
	v_pk_mul_f32 v[100:101], v[100:101], v[108:109]
	v_pk_mul_f32 v[98:99], v[98:99], v[114:115]
	s_and_b64 vcc, exec, s[42:43]
	s_mov_b64 s[0:1], -1
	s_cbranch_vccnz .LBB0_715
	s_mov_b32 s98, 0xbfb8aa3b
	s_mov_b32 s32, 0x437f0000
	v_pk_mul_f32 v[102:103], v[102:103], s[98:99] op_sel_hi:[1,0]
	v_pk_mul_f32 v[104:105], v[104:105], s[98:99] op_sel_hi:[1,0]
	v_pk_mul_f32 v[98:99], v[98:99], s[98:99] op_sel_hi:[1,0]
	v_pk_mul_f32 v[100:101], v[100:101], s[98:99] op_sel_hi:[1,0]
	v_exp_f32_e32 v102, v102
	v_exp_f32_e32 v103, v103
	v_exp_f32_e32 v104, v104
	v_exp_f32_e32 v105, v105
	v_exp_f32_e32 v98, v98
	v_exp_f32_e32 v99, v99
	v_exp_f32_e32 v100, v100
	v_exp_f32_e32 v101, v101
	v_pk_add_f32 v[102:103], v[102:103], 1.0 op_sel_hi:[1,0]
	v_pk_add_f32 v[104:105], v[104:105], 1.0 op_sel_hi:[1,0]
	v_pk_add_f32 v[98:99], v[98:99], 1.0 op_sel_hi:[1,0]
	v_pk_add_f32 v[100:101], v[100:101], 1.0 op_sel_hi:[1,0]
	v_rcp_f32_e32 v102, v102
	v_rcp_f32_e32 v103, v103
	v_rcp_f32_e32 v104, v104
	v_rcp_f32_e32 v105, v105
	v_rcp_f32_e32 v98, v98
	v_rcp_f32_e32 v99, v99
	v_rcp_f32_e32 v100, v100
	v_rcp_f32_e32 v101, v101
	v_pk_mul_f32 v[102:103], v[102:103], s[32:33] op_sel_hi:[1,0]
	v_pk_mul_f32 v[104:105], v[104:105], s[32:33] op_sel_hi:[1,0]
	v_pk_mul_f32 v[98:99], v[98:99], s[32:33] op_sel_hi:[1,0]
	v_pk_mul_f32 v[100:101], v[100:101], s[32:33] op_sel_hi:[1,0]
	v_max_f32_e32 v102, 1.0, v102
	v_max_f32_e32 v103, 1.0, v103
	v_max_f32_e32 v104, 1.0, v104
	v_max_f32_e32 v105, 1.0, v105
	v_max_f32_e32 v98, 1.0, v98
	v_max_f32_e32 v99, 1.0, v99
	v_max_f32_e32 v100, 1.0, v100
	v_max_f32_e32 v101, 1.0, v101
	v_rndne_f32_e32 v102, v102
	v_rndne_f32_e32 v103, v103
	v_rndne_f32_e32 v104, v104
	v_rndne_f32_e32 v105, v105
	v_rndne_f32_e32 v98, v98
	v_rndne_f32_e32 v99, v99
	v_rndne_f32_e32 v100, v100
	v_rndne_f32_e32 v101, v101
	v_cvt_pk_u8_f32 v108, v102, 0, 0
	v_cvt_pk_u8_f32 v108, v103, 1, v108
	v_cvt_pk_u8_f32 v109, v98, 0, 0
	v_cvt_pk_u8_f32 v109, v99, 1, v109
	v_cvt_pk_u8_f32 v108, v104, 2, v108
	v_cvt_pk_u8_f32 v108, v105, 3, v108
	v_cvt_pk_u8_f32 v109, v100, 2, v109
	v_cvt_pk_u8_f32 v109, v101, 3, v109
	v_mov_b64_e32 v[110:111], s[30:31]
	v_mad_i64_i32 v[110:111], s[0:1], v118, s55, v[110:111]
	v_lshl_add_u64 v[110:111], v[110:111], 0, v[140:141]
	s_mov_b64 s[0:1], 0
	v_mov_b32_e32 v244, v108
	v_mov_b32_e32 v245, v109
	v_mov_b32_e32 v250, v176
	v_mov_b32_e32 v251, 0
	v_lshl_add_u64 v[110:111], v[110:111], 0, v[250:251]
	global_store_dwordx4 v[110:111], v[244:247], off

.LBB0_717:
	v_ffbh_u32_e32 v98, v155
	v_min_u32_e32 v100, 32, v98
	v_lshlrev_b64 v[98:99], v100, v[154:155]
	v_min_u32_e32 v98, 1, v98
	v_or_b32_e32 v98, v99, v98
	v_cvt_f32_u32_e32 v98, v98
	v_sub_u32_e32 v99, 32, v100
	v_or_b32_e32 v102, 32, v142
	s_mov_b64 s[0:1], -1
	v_ldexp_f32 v98, v98, v99
	v_mul_f32_e32 v98, 0x33800000, v98
	v_fmamk_f32 v98, v98, 0x3a800000, v210
	s_nop 1
	v_rsq_f32_e32 v98, v98
	s_nop 0
	s_nop 0
	v_pk_mul_f32 v[96:97], v[96:97], v[98:99] op_sel_hi:[1,0]
	v_pk_mul_f32 v[100:101], v[94:95], v[98:99] op_sel_hi:[1,0]
	v_pk_mul_f32 v[92:93], v[92:93], v[98:99] op_sel_hi:[1,0]
	v_pk_mul_f32 v[94:95], v[90:91], v[98:99] op_sel_hi:[1,0]
	s_and_b64 vcc, exec, s[42:43]
	s_cbranch_vccnz .LBB0_719
	s_mov_b32 s98, 0xbfb8aa3b
	s_mov_b32 s32, 0x437f0000
	v_pk_mul_f32 v[100:101], v[100:101], s[98:99] op_sel_hi:[1,0]
	v_pk_mul_f32 v[96:97], v[96:97], s[98:99] op_sel_hi:[1,0]
	v_pk_mul_f32 v[94:95], v[94:95], s[98:99] op_sel_hi:[1,0]
	v_pk_mul_f32 v[92:93], v[92:93], s[98:99] op_sel_hi:[1,0]
	v_exp_f32_e32 v100, v100
	v_exp_f32_e32 v101, v101
	v_exp_f32_e32 v96, v96
	v_exp_f32_e32 v97, v97
	v_exp_f32_e32 v94, v94
	v_exp_f32_e32 v95, v95
	v_exp_f32_e32 v92, v92
	v_exp_f32_e32 v93, v93
	v_pk_add_f32 v[100:101], v[100:101], 1.0 op_sel_hi:[1,0]
	v_pk_add_f32 v[96:97], v[96:97], 1.0 op_sel_hi:[1,0]
	v_pk_add_f32 v[94:95], v[94:95], 1.0 op_sel_hi:[1,0]
	v_pk_add_f32 v[92:93], v[92:93], 1.0 op_sel_hi:[1,0]
	v_rcp_f32_e32 v100, v100
	v_rcp_f32_e32 v101, v101
	v_rcp_f32_e32 v96, v96
	v_rcp_f32_e32 v97, v97
	v_rcp_f32_e32 v94, v94
	v_rcp_f32_e32 v95, v95
	v_rcp_f32_e32 v92, v92
	v_rcp_f32_e32 v93, v93
	v_pk_mul_f32 v[100:101], v[100:101], s[32:33] op_sel_hi:[1,0]
	v_pk_mul_f32 v[96:97], v[96:97], s[32:33] op_sel_hi:[1,0]
	v_pk_mul_f32 v[94:95], v[94:95], s[32:33] op_sel_hi:[1,0]
	v_pk_mul_f32 v[92:93], v[92:93], s[32:33] op_sel_hi:[1,0]
	v_max_f32_e32 v100, 1.0, v100
	v_max_f32_e32 v101, 1.0, v101
	v_max_f32_e32 v96, 1.0, v96
	v_max_f32_e32 v97, 1.0, v97
	v_max_f32_e32 v94, 1.0, v94
	v_max_f32_e32 v95, 1.0, v95
	v_max_f32_e32 v92, 1.0, v92
	v_max_f32_e32 v93, 1.0, v93
	v_rndne_f32_e32 v100, v100
	v_rndne_f32_e32 v101, v101
	v_rndne_f32_e32 v96, v96
	v_rndne_f32_e32 v97, v97
	v_rndne_f32_e32 v94, v94
	v_rndne_f32_e32 v95, v95
	v_rndne_f32_e32 v92, v92
	v_rndne_f32_e32 v93, v93
	v_cvt_pk_u8_f32 v90, v100, 0, 0
	v_cvt_pk_u8_f32 v90, v101, 1, v90
	v_cvt_pk_u8_f32 v91, v94, 0, 0
	v_cvt_pk_u8_f32 v91, v95, 1, v91
	v_cvt_pk_u8_f32 v90, v96, 2, v90
	v_cvt_pk_u8_f32 v90, v97, 3, v90
	v_cvt_pk_u8_f32 v91, v92, 2, v91
	v_cvt_pk_u8_f32 v91, v93, 3, v91
	v_mov_b64_e32 v[104:105], s[30:31]
	v_mad_i64_i32 v[104:105], s[0:1], v102, s55, v[104:105]
	v_lshl_add_u64 v[104:105], v[104:105], 0, v[140:141]
	s_mov_b64 s[0:1], 0
	v_mov_b32_e32 v246, v90
	v_mov_b32_e32 v247, v91

.LBB0_721:
	v_mov_b32_e32 v99, v98
	v_mov_b32_e32 v92, v98
	v_mov_b32_e32 v93, v98
	v_pk_mul_f32 v[88:89], v[88:89], v[92:93]
	v_pk_mul_f32 v[86:87], v[86:87], v[98:99]
	v_pk_mul_f32 v[84:85], v[84:85], v[92:93]
	v_pk_mul_f32 v[82:83], v[82:83], v[98:99]
	s_and_b64 vcc, exec, s[42:43]
	s_mov_b64 s[0:1], -1
	s_cbranch_vccnz .LBB0_723
	s_mov_b32 s98, 0xbfb8aa3b
	s_mov_b32 s32, 0x437f0000
	v_pk_mul_f32 v[86:87], v[86:87], s[98:99] op_sel_hi:[1,0]
	v_pk_mul_f32 v[88:89], v[88:89], s[98:99] op_sel_hi:[1,0]
	v_pk_mul_f32 v[82:83], v[82:83], s[98:99] op_sel_hi:[1,0]
	v_pk_mul_f32 v[84:85], v[84:85], s[98:99] op_sel_hi:[1,0]
	v_exp_f32_e32 v86, v86
	v_exp_f32_e32 v87, v87
	v_exp_f32_e32 v88, v88
	v_exp_f32_e32 v89, v89
	v_exp_f32_e32 v82, v82
	v_exp_f32_e32 v83, v83
	v_exp_f32_e32 v84, v84
	v_exp_f32_e32 v85, v85
	v_pk_add_f32 v[86:87], v[86:87], 1.0 op_sel_hi:[1,0]
	v_pk_add_f32 v[88:89], v[88:89], 1.0 op_sel_hi:[1,0]
	v_pk_add_f32 v[82:83], v[82:83], 1.0 op_sel_hi:[1,0]
	v_pk_add_f32 v[84:85], v[84:85], 1.0 op_sel_hi:[1,0]
	v_rcp_f32_e32 v86, v86
	v_rcp_f32_e32 v87, v87
	v_rcp_f32_e32 v88, v88
	v_rcp_f32_e32 v89, v89
	v_rcp_f32_e32 v82, v82
	v_rcp_f32_e32 v83, v83
	v_rcp_f32_e32 v84, v84
	v_rcp_f32_e32 v85, v85
	v_pk_mul_f32 v[86:87], v[86:87], s[32:33] op_sel_hi:[1,0]
	v_pk_mul_f32 v[88:89], v[88:89], s[32:33] op_sel_hi:[1,0]
	v_pk_mul_f32 v[82:83], v[82:83], s[32:33] op_sel_hi:[1,0]
	v_pk_mul_f32 v[84:85], v[84:85], s[32:33] op_sel_hi:[1,0]
	v_max_f32_e32 v86, 1.0, v86
	v_max_f32_e32 v87, 1.0, v87
	v_max_f32_e32 v88, 1.0, v88
	v_max_f32_e32 v89, 1.0, v89
	v_max_f32_e32 v82, 1.0, v82
	v_max_f32_e32 v83, 1.0, v83
	v_max_f32_e32 v84, 1.0, v84
	v_max_f32_e32 v85, 1.0, v85
	v_rndne_f32_e32 v86, v86
	v_rndne_f32_e32 v87, v87
	v_rndne_f32_e32 v88, v88
	v_rndne_f32_e32 v89, v89
	v_rndne_f32_e32 v82, v82
	v_rndne_f32_e32 v83, v83
	v_rndne_f32_e32 v84, v84
	v_rndne_f32_e32 v85, v85
	v_cvt_pk_u8_f32 v92, v86, 0, 0
	v_cvt_pk_u8_f32 v92, v87, 1, v92
	v_cvt_pk_u8_f32 v93, v82, 0, 0
	v_cvt_pk_u8_f32 v93, v83, 1, v93
	v_cvt_pk_u8_f32 v92, v88, 2, v92
	v_cvt_pk_u8_f32 v92, v89, 3, v92
	v_cvt_pk_u8_f32 v93, v84, 2, v93
	v_cvt_pk_u8_f32 v93, v85, 3, v93
	v_mov_b64_e32 v[94:95], s[30:31]
	v_mad_i64_i32 v[94:95], s[0:1], v102, s55, v[94:95]
	v_lshl_add_u64 v[94:95], v[94:95], 0, v[140:141]
	s_mov_b64 s[0:1], 0
	v_mov_b32_e32 v244, v92
	v_mov_b32_e32 v245, v93
	v_mov_b32_e32 v250, v176
	v_mov_b32_e32 v251, 0
	v_lshl_add_u64 v[94:95], v[94:95], 0, v[250:251]
	global_store_dwordx4 v[94:95], v[244:247], off

.LBB0_725:
	v_ffbh_u32_e32 v82, v153
	v_min_u32_e32 v84, 32, v82
	v_lshlrev_b64 v[82:83], v84, v[152:153]
	v_min_u32_e32 v82, 1, v82
	v_or_b32_e32 v82, v83, v82
	v_cvt_f32_u32_e32 v82, v82
	v_sub_u32_e32 v83, 32, v84
	v_or_b32_e32 v86, 48, v142
	s_mov_b64 s[0:1], -1
	v_ldexp_f32 v82, v82, v83
	v_mul_f32_e32 v82, 0x33800000, v82
	v_fmamk_f32 v82, v82, 0x3a800000, v210
	s_nop 1
	v_rsq_f32_e32 v82, v82
	s_nop 0
	s_nop 0
	v_pk_mul_f32 v[80:81], v[80:81], v[82:83] op_sel_hi:[1,0]
	v_pk_mul_f32 v[84:85], v[78:79], v[82:83] op_sel_hi:[1,0]
	v_pk_mul_f32 v[76:77], v[76:77], v[82:83] op_sel_hi:[1,0]
	v_pk_mul_f32 v[78:79], v[74:75], v[82:83] op_sel_hi:[1,0]
	s_and_b64 vcc, exec, s[42:43]
	s_cbranch_vccnz .LBB0_727
	s_mov_b32 s98, 0xbfb8aa3b
	s_mov_b32 s32, 0x437f0000
	v_pk_mul_f32 v[84:85], v[84:85], s[98:99] op_sel_hi:[1,0]
	v_pk_mul_f32 v[80:81], v[80:81], s[98:99] op_sel_hi:[1,0]
	v_pk_mul_f32 v[78:79], v[78:79], s[98:99] op_sel_hi:[1,0]
	v_pk_mul_f32 v[76:77], v[76:77], s[98:99] op_sel_hi:[1,0]
	v_exp_f32_e32 v84, v84
	v_exp_f32_e32 v85, v85
	v_exp_f32_e32 v80, v80
	v_exp_f32_e32 v81, v81
	v_exp_f32_e32 v78, v78
	v_exp_f32_e32 v79, v79
	v_exp_f32_e32 v76, v76
	v_exp_f32_e32 v77, v77
	v_pk_add_f32 v[84:85], v[84:85], 1.0 op_sel_hi:[1,0]
	v_pk_add_f32 v[80:81], v[80:81], 1.0 op_sel_hi:[1,0]
	v_pk_add_f32 v[78:79], v[78:79], 1.0 op_sel_hi:[1,0]
	v_pk_add_f32 v[76:77], v[76:77], 1.0 op_sel_hi:[1,0]
	v_rcp_f32_e32 v84, v84
	v_rcp_f32_e32 v85, v85
	v_rcp_f32_e32 v80, v80
	v_rcp_f32_e32 v81, v81
	v_rcp_f32_e32 v78, v78
	v_rcp_f32_e32 v79, v79
	v_rcp_f32_e32 v76, v76
	v_rcp_f32_e32 v77, v77
	v_pk_mul_f32 v[84:85], v[84:85], s[32:33] op_sel_hi:[1,0]
	v_pk_mul_f32 v[80:81], v[80:81], s[32:33] op_sel_hi:[1,0]
	v_pk_mul_f32 v[78:79], v[78:79], s[32:33] op_sel_hi:[1,0]
	v_pk_mul_f32 v[76:77], v[76:77], s[32:33] op_sel_hi:[1,0]
	v_max_f32_e32 v84, 1.0, v84
	v_max_f32_e32 v85, 1.0, v85
	v_max_f32_e32 v80, 1.0, v80
	v_max_f32_e32 v81, 1.0, v81
	v_max_f32_e32 v78, 1.0, v78
	v_max_f32_e32 v79, 1.0, v79
	v_max_f32_e32 v76, 1.0, v76
	v_max_f32_e32 v77, 1.0, v77
	v_rndne_f32_e32 v84, v84
	v_rndne_f32_e32 v85, v85
	v_rndne_f32_e32 v80, v80
	v_rndne_f32_e32 v81, v81
	v_rndne_f32_e32 v78, v78
	v_rndne_f32_e32 v79, v79
	v_rndne_f32_e32 v76, v76
	v_rndne_f32_e32 v77, v77
	v_cvt_pk_u8_f32 v74, v84, 0, 0
	v_cvt_pk_u8_f32 v74, v85, 1, v74
	v_cvt_pk_u8_f32 v75, v78, 0, 0
	v_cvt_pk_u8_f32 v75, v79, 1, v75
	v_cvt_pk_u8_f32 v74, v80, 2, v74
	v_cvt_pk_u8_f32 v74, v81, 3, v74
	v_cvt_pk_u8_f32 v75, v76, 2, v75
	v_cvt_pk_u8_f32 v75, v77, 3, v75
	v_mov_b64_e32 v[88:89], s[30:31]
	v_mad_i64_i32 v[88:89], s[0:1], v86, s55, v[88:89]
	v_lshl_add_u64 v[88:89], v[88:89], 0, v[140:141]
	s_mov_b64 s[0:1], 0
	v_mov_b32_e32 v246, v74
	v_mov_b32_e32 v247, v75

.LBB0_729:
	v_mov_b32_e32 v83, v82
	v_mov_b32_e32 v76, v82
	v_mov_b32_e32 v77, v82
	v_pk_mul_f32 v[72:73], v[72:73], v[76:77]
	v_pk_mul_f32 v[70:71], v[70:71], v[82:83]
	v_pk_mul_f32 v[68:69], v[68:69], v[76:77]
	v_pk_mul_f32 v[66:67], v[66:67], v[82:83]
	s_and_b64 vcc, exec, s[42:43]
	s_mov_b64 s[0:1], -1
	s_cbranch_vccnz .LBB0_731
	s_mov_b32 s98, 0xbfb8aa3b
	s_mov_b32 s32, 0x437f0000
	v_pk_mul_f32 v[70:71], v[70:71], s[98:99] op_sel_hi:[1,0]
	v_pk_mul_f32 v[72:73], v[72:73], s[98:99] op_sel_hi:[1,0]
	v_pk_mul_f32 v[66:67], v[66:67], s[98:99] op_sel_hi:[1,0]
	v_pk_mul_f32 v[68:69], v[68:69], s[98:99] op_sel_hi:[1,0]
	v_exp_f32_e32 v70, v70
	v_exp_f32_e32 v71, v71
	v_exp_f32_e32 v72, v72
	v_exp_f32_e32 v73, v73
	v_exp_f32_e32 v66, v66
	v_exp_f32_e32 v67, v67
	v_exp_f32_e32 v68, v68
	v_exp_f32_e32 v69, v69
	v_pk_add_f32 v[70:71], v[70:71], 1.0 op_sel_hi:[1,0]
	v_pk_add_f32 v[72:73], v[72:73], 1.0 op_sel_hi:[1,0]
	v_pk_add_f32 v[66:67], v[66:67], 1.0 op_sel_hi:[1,0]
	v_pk_add_f32 v[68:69], v[68:69], 1.0 op_sel_hi:[1,0]
	v_rcp_f32_e32 v70, v70
	v_rcp_f32_e32 v71, v71
	v_rcp_f32_e32 v72, v72
	v_rcp_f32_e32 v73, v73
	v_rcp_f32_e32 v66, v66
	v_rcp_f32_e32 v67, v67
	v_rcp_f32_e32 v68, v68
	v_rcp_f32_e32 v69, v69
	v_pk_mul_f32 v[70:71], v[70:71], s[32:33] op_sel_hi:[1,0]
	v_pk_mul_f32 v[72:73], v[72:73], s[32:33] op_sel_hi:[1,0]
	v_pk_mul_f32 v[66:67], v[66:67], s[32:33] op_sel_hi:[1,0]
	v_pk_mul_f32 v[68:69], v[68:69], s[32:33] op_sel_hi:[1,0]
	v_max_f32_e32 v70, 1.0, v70
	v_max_f32_e32 v71, 1.0, v71
	v_max_f32_e32 v72, 1.0, v72
	v_max_f32_e32 v73, 1.0, v73
	v_max_f32_e32 v66, 1.0, v66
	v_max_f32_e32 v67, 1.0, v67
	v_max_f32_e32 v68, 1.0, v68
	v_max_f32_e32 v69, 1.0, v69
	v_rndne_f32_e32 v70, v70
	v_rndne_f32_e32 v71, v71
	v_rndne_f32_e32 v72, v72
	v_rndne_f32_e32 v73, v73
	v_rndne_f32_e32 v66, v66
	v_rndne_f32_e32 v67, v67
	v_rndne_f32_e32 v68, v68
	v_rndne_f32_e32 v69, v69
	v_cvt_pk_u8_f32 v76, v70, 0, 0
	v_cvt_pk_u8_f32 v76, v71, 1, v76
	v_cvt_pk_u8_f32 v77, v66, 0, 0
	v_cvt_pk_u8_f32 v77, v67, 1, v77
	v_cvt_pk_u8_f32 v76, v72, 2, v76
	v_cvt_pk_u8_f32 v76, v73, 3, v76
	v_cvt_pk_u8_f32 v77, v68, 2, v77
	v_cvt_pk_u8_f32 v77, v69, 3, v77
	v_mov_b64_e32 v[78:79], s[30:31]
	v_mad_i64_i32 v[78:79], s[0:1], v86, s55, v[78:79]
	v_lshl_add_u64 v[78:79], v[78:79], 0, v[140:141]
	s_mov_b64 s[0:1], 0
	v_mov_b32_e32 v244, v76
	v_mov_b32_e32 v245, v77
	v_mov_b32_e32 v250, v176
	v_mov_b32_e32 v251, 0
	v_lshl_add_u64 v[78:79], v[78:79], 0, v[250:251]
	global_store_dwordx4 v[78:79], v[244:247], off

.LBB0_733:
	v_ffbh_u32_e32 v66, v151
	v_min_u32_e32 v68, 32, v66
	v_lshlrev_b64 v[66:67], v68, v[150:151]
	v_min_u32_e32 v66, 1, v66
	v_or_b32_e32 v66, v67, v66
	v_cvt_f32_u32_e32 v66, v66
	v_sub_u32_e32 v67, 32, v68
	v_add_u32_e32 v70, 0x80, v142
	s_mov_b64 s[0:1], -1
	v_ldexp_f32 v66, v66, v67
	v_mul_f32_e32 v66, 0x33800000, v66
	v_fmamk_f32 v66, v66, 0x3a800000, v210
	s_nop 1
	v_rsq_f32_e32 v66, v66
	s_nop 0
	s_nop 0
	v_pk_mul_f32 v[64:65], v[64:65], v[66:67] op_sel_hi:[1,0]
	v_pk_mul_f32 v[68:69], v[62:63], v[66:67] op_sel_hi:[1,0]
	v_pk_mul_f32 v[60:61], v[60:61], v[66:67] op_sel_hi:[1,0]
	v_pk_mul_f32 v[62:63], v[58:59], v[66:67] op_sel_hi:[1,0]
	s_and_b64 vcc, exec, s[42:43]
	s_cbranch_vccnz .LBB0_735
	s_mov_b32 s98, 0xbfb8aa3b
	s_mov_b32 s32, 0x437f0000
	v_pk_mul_f32 v[68:69], v[68:69], s[98:99] op_sel_hi:[1,0]
	v_pk_mul_f32 v[64:65], v[64:65], s[98:99] op_sel_hi:[1,0]
	v_pk_mul_f32 v[62:63], v[62:63], s[98:99] op_sel_hi:[1,0]
	v_pk_mul_f32 v[60:61], v[60:61], s[98:99] op_sel_hi:[1,0]
	v_exp_f32_e32 v68, v68
	v_exp_f32_e32 v69, v69
	v_exp_f32_e32 v64, v64
	v_exp_f32_e32 v65, v65
	v_exp_f32_e32 v62, v62
	v_exp_f32_e32 v63, v63
	v_exp_f32_e32 v60, v60
	v_exp_f32_e32 v61, v61
	v_pk_add_f32 v[68:69], v[68:69], 1.0 op_sel_hi:[1,0]
	v_pk_add_f32 v[64:65], v[64:65], 1.0 op_sel_hi:[1,0]
	v_pk_add_f32 v[62:63], v[62:63], 1.0 op_sel_hi:[1,0]
	v_pk_add_f32 v[60:61], v[60:61], 1.0 op_sel_hi:[1,0]
	v_rcp_f32_e32 v68, v68
	v_rcp_f32_e32 v69, v69
	v_rcp_f32_e32 v64, v64
	v_rcp_f32_e32 v65, v65
	v_rcp_f32_e32 v62, v62
	v_rcp_f32_e32 v63, v63
	v_rcp_f32_e32 v60, v60
	v_rcp_f32_e32 v61, v61
	v_pk_mul_f32 v[68:69], v[68:69], s[32:33] op_sel_hi:[1,0]
	v_pk_mul_f32 v[64:65], v[64:65], s[32:33] op_sel_hi:[1,0]
	v_pk_mul_f32 v[62:63], v[62:63], s[32:33] op_sel_hi:[1,0]
	v_pk_mul_f32 v[60:61], v[60:61], s[32:33] op_sel_hi:[1,0]
	v_max_f32_e32 v68, 1.0, v68
	v_max_f32_e32 v69, 1.0, v69
	v_max_f32_e32 v64, 1.0, v64
	v_max_f32_e32 v65, 1.0, v65
	v_max_f32_e32 v62, 1.0, v62
	v_max_f32_e32 v63, 1.0, v63
	v_max_f32_e32 v60, 1.0, v60
	v_max_f32_e32 v61, 1.0, v61
	v_rndne_f32_e32 v68, v68
	v_rndne_f32_e32 v69, v69
	v_rndne_f32_e32 v64, v64
	v_rndne_f32_e32 v65, v65
	v_rndne_f32_e32 v62, v62
	v_rndne_f32_e32 v63, v63
	v_rndne_f32_e32 v60, v60
	v_rndne_f32_e32 v61, v61
	v_cvt_pk_u8_f32 v58, v68, 0, 0
	v_cvt_pk_u8_f32 v58, v69, 1, v58
	v_cvt_pk_u8_f32 v59, v62, 0, 0
	v_cvt_pk_u8_f32 v59, v63, 1, v59
	v_cvt_pk_u8_f32 v58, v64, 2, v58
	v_cvt_pk_u8_f32 v58, v65, 3, v58
	v_cvt_pk_u8_f32 v59, v60, 2, v59
	v_cvt_pk_u8_f32 v59, v61, 3, v59
	v_mov_b64_e32 v[72:73], s[30:31]
	v_mad_i64_i32 v[72:73], s[0:1], v70, s55, v[72:73]
	v_lshl_add_u64 v[72:73], v[72:73], 0, v[140:141]
	s_mov_b64 s[0:1], 0
	v_mov_b32_e32 v246, v58
	v_mov_b32_e32 v247, v59

.LBB0_737:
	v_mov_b32_e32 v67, v66
	v_mov_b32_e32 v60, v66
	v_mov_b32_e32 v61, v66
	v_pk_mul_f32 v[56:57], v[56:57], v[60:61]
	v_pk_mul_f32 v[54:55], v[54:55], v[66:67]
	v_pk_mul_f32 v[52:53], v[52:53], v[60:61]
	v_pk_mul_f32 v[50:51], v[50:51], v[66:67]
	s_and_b64 vcc, exec, s[42:43]
	s_mov_b64 s[0:1], -1
	s_cbranch_vccnz .LBB0_739
	s_mov_b32 s98, 0xbfb8aa3b
	s_mov_b32 s32, 0x437f0000
	v_pk_mul_f32 v[54:55], v[54:55], s[98:99] op_sel_hi:[1,0]
	v_pk_mul_f32 v[56:57], v[56:57], s[98:99] op_sel_hi:[1,0]
	v_pk_mul_f32 v[50:51], v[50:51], s[98:99] op_sel_hi:[1,0]
	v_pk_mul_f32 v[52:53], v[52:53], s[98:99] op_sel_hi:[1,0]
	v_exp_f32_e32 v54, v54
	v_exp_f32_e32 v55, v55
	v_exp_f32_e32 v56, v56
	v_exp_f32_e32 v57, v57
	v_exp_f32_e32 v50, v50
	v_exp_f32_e32 v51, v51
	v_exp_f32_e32 v52, v52
	v_exp_f32_e32 v53, v53
	v_pk_add_f32 v[54:55], v[54:55], 1.0 op_sel_hi:[1,0]
	v_pk_add_f32 v[56:57], v[56:57], 1.0 op_sel_hi:[1,0]
	v_pk_add_f32 v[50:51], v[50:51], 1.0 op_sel_hi:[1,0]
	v_pk_add_f32 v[52:53], v[52:53], 1.0 op_sel_hi:[1,0]
	v_rcp_f32_e32 v54, v54
	v_rcp_f32_e32 v55, v55
	v_rcp_f32_e32 v56, v56
	v_rcp_f32_e32 v57, v57
	v_rcp_f32_e32 v50, v50
	v_rcp_f32_e32 v51, v51
	v_rcp_f32_e32 v52, v52
	v_rcp_f32_e32 v53, v53
	v_pk_mul_f32 v[54:55], v[54:55], s[32:33] op_sel_hi:[1,0]
	v_pk_mul_f32 v[56:57], v[56:57], s[32:33] op_sel_hi:[1,0]
	v_pk_mul_f32 v[50:51], v[50:51], s[32:33] op_sel_hi:[1,0]
	v_pk_mul_f32 v[52:53], v[52:53], s[32:33] op_sel_hi:[1,0]
	v_max_f32_e32 v54, 1.0, v54
	v_max_f32_e32 v55, 1.0, v55
	v_max_f32_e32 v56, 1.0, v56
	v_max_f32_e32 v57, 1.0, v57
	v_max_f32_e32 v50, 1.0, v50
	v_max_f32_e32 v51, 1.0, v51
	v_max_f32_e32 v52, 1.0, v52
	v_max_f32_e32 v53, 1.0, v53
	v_rndne_f32_e32 v54, v54
	v_rndne_f32_e32 v55, v55
	v_rndne_f32_e32 v56, v56
	v_rndne_f32_e32 v57, v57
	v_rndne_f32_e32 v50, v50
	v_rndne_f32_e32 v51, v51
	v_rndne_f32_e32 v52, v52
	v_rndne_f32_e32 v53, v53
	v_cvt_pk_u8_f32 v60, v54, 0, 0
	v_cvt_pk_u8_f32 v60, v55, 1, v60
	v_cvt_pk_u8_f32 v61, v50, 0, 0
	v_cvt_pk_u8_f32 v61, v51, 1, v61
	v_cvt_pk_u8_f32 v60, v56, 2, v60
	v_cvt_pk_u8_f32 v60, v57, 3, v60
	v_cvt_pk_u8_f32 v61, v52, 2, v61
	v_cvt_pk_u8_f32 v61, v53, 3, v61
	v_mov_b64_e32 v[62:63], s[30:31]
	v_mad_i64_i32 v[62:63], s[0:1], v70, s55, v[62:63]
	v_lshl_add_u64 v[62:63], v[62:63], 0, v[140:141]
	s_mov_b64 s[0:1], 0
	v_mov_b32_e32 v244, v60
	v_mov_b32_e32 v245, v61
	v_mov_b32_e32 v250, v176
	v_mov_b32_e32 v251, 0
	v_lshl_add_u64 v[62:63], v[62:63], 0, v[250:251]
	global_store_dwordx4 v[62:63], v[244:247], off

.LBB0_741:
	v_ffbh_u32_e32 v50, v149
	v_min_u32_e32 v52, 32, v50
	v_lshlrev_b64 v[50:51], v52, v[148:149]
	v_min_u32_e32 v50, 1, v50
	v_or_b32_e32 v50, v51, v50
	v_cvt_f32_u32_e32 v50, v50
	v_sub_u32_e32 v51, 32, v52
	v_add_u32_e32 v54, 0x90, v142
	s_mov_b64 s[0:1], -1
	v_ldexp_f32 v50, v50, v51
	v_mul_f32_e32 v50, 0x33800000, v50
	v_fmamk_f32 v50, v50, 0x3a800000, v210
	s_nop 1
	v_rsq_f32_e32 v50, v50
	s_nop 0
	s_nop 0
	v_pk_mul_f32 v[48:49], v[48:49], v[50:51] op_sel_hi:[1,0]
	v_pk_mul_f32 v[52:53], v[46:47], v[50:51] op_sel_hi:[1,0]
	v_pk_mul_f32 v[44:45], v[44:45], v[50:51] op_sel_hi:[1,0]
	v_pk_mul_f32 v[46:47], v[42:43], v[50:51] op_sel_hi:[1,0]
	s_and_b64 vcc, exec, s[42:43]
	s_cbranch_vccnz .LBB0_743
	s_mov_b32 s98, 0xbfb8aa3b
	s_mov_b32 s32, 0x437f0000
	v_pk_mul_f32 v[52:53], v[52:53], s[98:99] op_sel_hi:[1,0]
	v_pk_mul_f32 v[48:49], v[48:49], s[98:99] op_sel_hi:[1,0]
	v_pk_mul_f32 v[46:47], v[46:47], s[98:99] op_sel_hi:[1,0]
	v_pk_mul_f32 v[44:45], v[44:45], s[98:99] op_sel_hi:[1,0]
	v_exp_f32_e32 v52, v52
	v_exp_f32_e32 v53, v53
	v_exp_f32_e32 v48, v48
	v_exp_f32_e32 v49, v49
	v_exp_f32_e32 v46, v46
	v_exp_f32_e32 v47, v47
	v_exp_f32_e32 v44, v44
	v_exp_f32_e32 v45, v45
	v_pk_add_f32 v[52:53], v[52:53], 1.0 op_sel_hi:[1,0]
	v_pk_add_f32 v[48:49], v[48:49], 1.0 op_sel_hi:[1,0]
	v_pk_add_f32 v[46:47], v[46:47], 1.0 op_sel_hi:[1,0]
	v_pk_add_f32 v[44:45], v[44:45], 1.0 op_sel_hi:[1,0]
	v_rcp_f32_e32 v52, v52
	v_rcp_f32_e32 v53, v53
	v_rcp_f32_e32 v48, v48
	v_rcp_f32_e32 v49, v49
	v_rcp_f32_e32 v46, v46
	v_rcp_f32_e32 v47, v47
	v_rcp_f32_e32 v44, v44
	v_rcp_f32_e32 v45, v45
	v_pk_mul_f32 v[52:53], v[52:53], s[32:33] op_sel_hi:[1,0]
	v_pk_mul_f32 v[48:49], v[48:49], s[32:33] op_sel_hi:[1,0]
	v_pk_mul_f32 v[46:47], v[46:47], s[32:33] op_sel_hi:[1,0]
	v_pk_mul_f32 v[44:45], v[44:45], s[32:33] op_sel_hi:[1,0]
	v_max_f32_e32 v52, 1.0, v52
	v_max_f32_e32 v53, 1.0, v53
	v_max_f32_e32 v48, 1.0, v48
	v_max_f32_e32 v49, 1.0, v49
	v_max_f32_e32 v46, 1.0, v46
	v_max_f32_e32 v47, 1.0, v47
	v_max_f32_e32 v44, 1.0, v44
	v_max_f32_e32 v45, 1.0, v45
	v_rndne_f32_e32 v52, v52
	v_rndne_f32_e32 v53, v53
	v_rndne_f32_e32 v48, v48
	v_rndne_f32_e32 v49, v49
	v_rndne_f32_e32 v46, v46
	v_rndne_f32_e32 v47, v47
	v_rndne_f32_e32 v44, v44
	v_rndne_f32_e32 v45, v45
	v_cvt_pk_u8_f32 v42, v52, 0, 0
	v_cvt_pk_u8_f32 v42, v53, 1, v42
	v_cvt_pk_u8_f32 v43, v46, 0, 0
	v_cvt_pk_u8_f32 v43, v47, 1, v43
	v_cvt_pk_u8_f32 v42, v48, 2, v42
	v_cvt_pk_u8_f32 v42, v49, 3, v42
	v_cvt_pk_u8_f32 v43, v44, 2, v43
	v_cvt_pk_u8_f32 v43, v45, 3, v43
	v_mov_b64_e32 v[56:57], s[30:31]
	v_mad_i64_i32 v[56:57], s[0:1], v54, s55, v[56:57]
	v_lshl_add_u64 v[56:57], v[56:57], 0, v[140:141]
	s_mov_b64 s[0:1], 0
	v_mov_b32_e32 v246, v42
	v_mov_b32_e32 v247, v43

.LBB0_745:
	v_mov_b32_e32 v51, v50
	v_mov_b32_e32 v44, v50
	v_mov_b32_e32 v45, v50
	v_pk_mul_f32 v[40:41], v[40:41], v[44:45]
	v_pk_mul_f32 v[38:39], v[38:39], v[50:51]
	v_pk_mul_f32 v[36:37], v[36:37], v[44:45]
	v_pk_mul_f32 v[34:35], v[34:35], v[50:51]
	s_and_b64 vcc, exec, s[42:43]
	s_mov_b64 s[0:1], -1
	s_cbranch_vccnz .LBB0_747
	s_mov_b32 s98, 0xbfb8aa3b
	s_mov_b32 s32, 0x437f0000
	v_pk_mul_f32 v[38:39], v[38:39], s[98:99] op_sel_hi:[1,0]
	v_pk_mul_f32 v[40:41], v[40:41], s[98:99] op_sel_hi:[1,0]
	v_pk_mul_f32 v[34:35], v[34:35], s[98:99] op_sel_hi:[1,0]
	v_pk_mul_f32 v[36:37], v[36:37], s[98:99] op_sel_hi:[1,0]
	v_exp_f32_e32 v38, v38
	v_exp_f32_e32 v39, v39
	v_exp_f32_e32 v40, v40
	v_exp_f32_e32 v41, v41
	v_exp_f32_e32 v34, v34
	v_exp_f32_e32 v35, v35
	v_exp_f32_e32 v36, v36
	v_exp_f32_e32 v37, v37
	v_pk_add_f32 v[38:39], v[38:39], 1.0 op_sel_hi:[1,0]
	v_pk_add_f32 v[40:41], v[40:41], 1.0 op_sel_hi:[1,0]
	v_pk_add_f32 v[34:35], v[34:35], 1.0 op_sel_hi:[1,0]
	v_pk_add_f32 v[36:37], v[36:37], 1.0 op_sel_hi:[1,0]
	v_rcp_f32_e32 v38, v38
	v_rcp_f32_e32 v39, v39
	v_rcp_f32_e32 v40, v40
	v_rcp_f32_e32 v41, v41
	v_rcp_f32_e32 v34, v34
	v_rcp_f32_e32 v35, v35
	v_rcp_f32_e32 v36, v36
	v_rcp_f32_e32 v37, v37
	v_pk_mul_f32 v[38:39], v[38:39], s[32:33] op_sel_hi:[1,0]
	v_pk_mul_f32 v[40:41], v[40:41], s[32:33] op_sel_hi:[1,0]
	v_pk_mul_f32 v[34:35], v[34:35], s[32:33] op_sel_hi:[1,0]
	v_pk_mul_f32 v[36:37], v[36:37], s[32:33] op_sel_hi:[1,0]
	v_max_f32_e32 v38, 1.0, v38
	v_max_f32_e32 v39, 1.0, v39
	v_max_f32_e32 v40, 1.0, v40
	v_max_f32_e32 v41, 1.0, v41
	v_max_f32_e32 v34, 1.0, v34
	v_max_f32_e32 v35, 1.0, v35
	v_max_f32_e32 v36, 1.0, v36
	v_max_f32_e32 v37, 1.0, v37
	v_rndne_f32_e32 v38, v38
	v_rndne_f32_e32 v39, v39
	v_rndne_f32_e32 v40, v40
	v_rndne_f32_e32 v41, v41
	v_rndne_f32_e32 v34, v34
	v_rndne_f32_e32 v35, v35
	v_rndne_f32_e32 v36, v36
	v_rndne_f32_e32 v37, v37
	v_cvt_pk_u8_f32 v44, v38, 0, 0
	v_cvt_pk_u8_f32 v44, v39, 1, v44
	v_cvt_pk_u8_f32 v45, v34, 0, 0
	v_cvt_pk_u8_f32 v45, v35, 1, v45
	v_cvt_pk_u8_f32 v44, v40, 2, v44
	v_cvt_pk_u8_f32 v44, v41, 3, v44
	v_cvt_pk_u8_f32 v45, v36, 2, v45
	v_cvt_pk_u8_f32 v45, v37, 3, v45
	v_mov_b64_e32 v[46:47], s[30:31]
	v_mad_i64_i32 v[46:47], s[0:1], v54, s55, v[46:47]
	v_lshl_add_u64 v[46:47], v[46:47], 0, v[140:141]
	s_mov_b64 s[0:1], 0
	v_mov_b32_e32 v244, v44
	v_mov_b32_e32 v245, v45
	v_mov_b32_e32 v250, v176
	v_mov_b32_e32 v251, 0
	v_lshl_add_u64 v[46:47], v[46:47], 0, v[250:251]
	global_store_dwordx4 v[46:47], v[244:247], off

.LBB0_749:
	v_ffbh_u32_e32 v34, v147
	v_min_u32_e32 v36, 32, v34
	v_lshlrev_b64 v[34:35], v36, v[146:147]
	v_min_u32_e32 v34, 1, v34
	v_or_b32_e32 v34, v35, v34
	v_cvt_f32_u32_e32 v34, v34
	v_sub_u32_e32 v35, 32, v36
	v_add_u32_e32 v38, 0xa0, v142
	s_mov_b64 s[0:1], -1
	v_ldexp_f32 v34, v34, v35
	v_mul_f32_e32 v34, 0x33800000, v34
	v_fmamk_f32 v34, v34, 0x3a800000, v210
	s_nop 1
	v_rsq_f32_e32 v34, v34
	s_nop 0
	s_nop 0
	v_pk_mul_f32 v[32:33], v[32:33], v[34:35] op_sel_hi:[1,0]
	v_pk_mul_f32 v[36:37], v[30:31], v[34:35] op_sel_hi:[1,0]
	v_pk_mul_f32 v[28:29], v[28:29], v[34:35] op_sel_hi:[1,0]
	v_pk_mul_f32 v[30:31], v[26:27], v[34:35] op_sel_hi:[1,0]
	s_and_b64 vcc, exec, s[42:43]
	s_cbranch_vccnz .LBB0_751
	s_mov_b32 s98, 0xbfb8aa3b
	s_mov_b32 s32, 0x437f0000
	v_pk_mul_f32 v[36:37], v[36:37], s[98:99] op_sel_hi:[1,0]
	v_pk_mul_f32 v[32:33], v[32:33], s[98:99] op_sel_hi:[1,0]
	v_pk_mul_f32 v[30:31], v[30:31], s[98:99] op_sel_hi:[1,0]
	v_pk_mul_f32 v[28:29], v[28:29], s[98:99] op_sel_hi:[1,0]
	v_exp_f32_e32 v36, v36
	v_exp_f32_e32 v37, v37
	v_exp_f32_e32 v32, v32
	v_exp_f32_e32 v33, v33
	v_exp_f32_e32 v30, v30
	v_exp_f32_e32 v31, v31
	v_exp_f32_e32 v28, v28
	v_exp_f32_e32 v29, v29
	v_pk_add_f32 v[36:37], v[36:37], 1.0 op_sel_hi:[1,0]
	v_pk_add_f32 v[32:33], v[32:33], 1.0 op_sel_hi:[1,0]
	v_pk_add_f32 v[30:31], v[30:31], 1.0 op_sel_hi:[1,0]
	v_pk_add_f32 v[28:29], v[28:29], 1.0 op_sel_hi:[1,0]
	v_rcp_f32_e32 v36, v36
	v_rcp_f32_e32 v37, v37
	v_rcp_f32_e32 v32, v32
	v_rcp_f32_e32 v33, v33
	v_rcp_f32_e32 v30, v30
	v_rcp_f32_e32 v31, v31
	v_rcp_f32_e32 v28, v28
	v_rcp_f32_e32 v29, v29
	v_pk_mul_f32 v[36:37], v[36:37], s[32:33] op_sel_hi:[1,0]
	v_pk_mul_f32 v[32:33], v[32:33], s[32:33] op_sel_hi:[1,0]
	v_pk_mul_f32 v[30:31], v[30:31], s[32:33] op_sel_hi:[1,0]
	v_pk_mul_f32 v[28:29], v[28:29], s[32:33] op_sel_hi:[1,0]
	v_max_f32_e32 v36, 1.0, v36
	v_max_f32_e32 v37, 1.0, v37
	v_max_f32_e32 v32, 1.0, v32
	v_max_f32_e32 v33, 1.0, v33
	v_max_f32_e32 v30, 1.0, v30
	v_max_f32_e32 v31, 1.0, v31
	v_max_f32_e32 v28, 1.0, v28
	v_max_f32_e32 v29, 1.0, v29
	v_rndne_f32_e32 v36, v36
	v_rndne_f32_e32 v37, v37
	v_rndne_f32_e32 v32, v32
	v_rndne_f32_e32 v33, v33
	v_rndne_f32_e32 v30, v30
	v_rndne_f32_e32 v31, v31
	v_rndne_f32_e32 v28, v28
	v_rndne_f32_e32 v29, v29
	v_cvt_pk_u8_f32 v26, v36, 0, 0
	v_cvt_pk_u8_f32 v26, v37, 1, v26
	v_cvt_pk_u8_f32 v27, v30, 0, 0
	v_cvt_pk_u8_f32 v27, v31, 1, v27
	v_cvt_pk_u8_f32 v26, v32, 2, v26
	v_cvt_pk_u8_f32 v26, v33, 3, v26
	v_cvt_pk_u8_f32 v27, v28, 2, v27
	v_cvt_pk_u8_f32 v27, v29, 3, v27
	v_mov_b64_e32 v[40:41], s[30:31]
	v_mad_i64_i32 v[40:41], s[0:1], v38, s55, v[40:41]
	v_lshl_add_u64 v[40:41], v[40:41], 0, v[140:141]
	s_mov_b64 s[0:1], 0
	v_mov_b32_e32 v246, v26
	v_mov_b32_e32 v247, v27

.LBB0_753:
	v_mov_b32_e32 v35, v34
	v_mov_b32_e32 v28, v34
	v_mov_b32_e32 v29, v34
	v_pk_mul_f32 v[24:25], v[24:25], v[28:29]
	v_pk_mul_f32 v[22:23], v[22:23], v[34:35]
	v_pk_mul_f32 v[20:21], v[20:21], v[28:29]
	v_pk_mul_f32 v[18:19], v[18:19], v[34:35]
	s_and_b64 vcc, exec, s[42:43]
	s_mov_b64 s[0:1], -1
	s_cbranch_vccnz .LBB0_755
	s_mov_b32 s98, 0xbfb8aa3b
	s_mov_b32 s32, 0x437f0000
	v_pk_mul_f32 v[22:23], v[22:23], s[98:99] op_sel_hi:[1,0]
	v_pk_mul_f32 v[24:25], v[24:25], s[98:99] op_sel_hi:[1,0]
	v_pk_mul_f32 v[18:19], v[18:19], s[98:99] op_sel_hi:[1,0]
	v_pk_mul_f32 v[20:21], v[20:21], s[98:99] op_sel_hi:[1,0]
	v_exp_f32_e32 v22, v22
	v_exp_f32_e32 v23, v23
	v_exp_f32_e32 v24, v24
	v_exp_f32_e32 v25, v25
	v_exp_f32_e32 v18, v18
	v_exp_f32_e32 v19, v19
	v_exp_f32_e32 v20, v20
	v_exp_f32_e32 v21, v21
	v_pk_add_f32 v[22:23], v[22:23], 1.0 op_sel_hi:[1,0]
	v_pk_add_f32 v[24:25], v[24:25], 1.0 op_sel_hi:[1,0]
	v_pk_add_f32 v[18:19], v[18:19], 1.0 op_sel_hi:[1,0]
	v_pk_add_f32 v[20:21], v[20:21], 1.0 op_sel_hi:[1,0]
	v_rcp_f32_e32 v22, v22
	v_rcp_f32_e32 v23, v23
	v_rcp_f32_e32 v24, v24
	v_rcp_f32_e32 v25, v25
	v_rcp_f32_e32 v18, v18
	v_rcp_f32_e32 v19, v19
	v_rcp_f32_e32 v20, v20
	v_rcp_f32_e32 v21, v21
	v_pk_mul_f32 v[22:23], v[22:23], s[32:33] op_sel_hi:[1,0]
	v_pk_mul_f32 v[24:25], v[24:25], s[32:33] op_sel_hi:[1,0]
	v_pk_mul_f32 v[18:19], v[18:19], s[32:33] op_sel_hi:[1,0]
	v_pk_mul_f32 v[20:21], v[20:21], s[32:33] op_sel_hi:[1,0]
	v_max_f32_e32 v22, 1.0, v22
	v_max_f32_e32 v23, 1.0, v23
	v_max_f32_e32 v24, 1.0, v24
	v_max_f32_e32 v25, 1.0, v25
	v_max_f32_e32 v18, 1.0, v18
	v_max_f32_e32 v19, 1.0, v19
	v_max_f32_e32 v20, 1.0, v20
	v_max_f32_e32 v21, 1.0, v21
	v_rndne_f32_e32 v22, v22
	v_rndne_f32_e32 v23, v23
	v_rndne_f32_e32 v24, v24
	v_rndne_f32_e32 v25, v25
	v_rndne_f32_e32 v18, v18
	v_rndne_f32_e32 v19, v19
	v_rndne_f32_e32 v20, v20
	v_rndne_f32_e32 v21, v21
	v_cvt_pk_u8_f32 v28, v22, 0, 0
	v_cvt_pk_u8_f32 v28, v23, 1, v28
	v_cvt_pk_u8_f32 v29, v18, 0, 0
	v_cvt_pk_u8_f32 v29, v19, 1, v29
	v_cvt_pk_u8_f32 v28, v24, 2, v28
	v_cvt_pk_u8_f32 v28, v25, 3, v28
	v_cvt_pk_u8_f32 v29, v20, 2, v29
	v_cvt_pk_u8_f32 v29, v21, 3, v29
	v_mov_b64_e32 v[30:31], s[30:31]
	v_mad_i64_i32 v[30:31], s[0:1], v38, s55, v[30:31]
	v_lshl_add_u64 v[30:31], v[30:31], 0, v[140:141]
	s_mov_b64 s[0:1], 0
	v_mov_b32_e32 v244, v28
	v_mov_b32_e32 v245, v29
	v_mov_b32_e32 v250, v176
	v_mov_b32_e32 v251, 0
	v_lshl_add_u64 v[30:31], v[30:31], 0, v[250:251]
	global_store_dwordx4 v[30:31], v[244:247], off

.LBB0_757:
	v_ffbh_u32_e32 v18, v145
	v_min_u32_e32 v20, 32, v18
	v_lshlrev_b64 v[18:19], v20, v[144:145]
	v_min_u32_e32 v18, 1, v18
	v_or_b32_e32 v18, v19, v18
	v_cvt_f32_u32_e32 v18, v18
	v_sub_u32_e32 v19, 32, v20
	v_add_u32_e32 v22, 0xb0, v142
	s_mov_b64 s[0:1], -1
	v_ldexp_f32 v18, v18, v19
	v_mul_f32_e32 v18, 0x33800000, v18
	v_fmamk_f32 v18, v18, 0x3a800000, v210
	s_nop 1
	v_rsq_f32_e32 v18, v18
	s_nop 0
	s_nop 0
	v_pk_mul_f32 v[16:17], v[16:17], v[18:19] op_sel_hi:[1,0]
	v_pk_mul_f32 v[20:21], v[14:15], v[18:19] op_sel_hi:[1,0]
	v_pk_mul_f32 v[12:13], v[12:13], v[18:19] op_sel_hi:[1,0]
	v_pk_mul_f32 v[14:15], v[10:11], v[18:19] op_sel_hi:[1,0]
	s_and_b64 vcc, exec, s[42:43]
	s_cbranch_vccnz .LBB0_759
	s_mov_b32 s98, 0xbfb8aa3b
	s_mov_b32 s32, 0x437f0000
	v_pk_mul_f32 v[20:21], v[20:21], s[98:99] op_sel_hi:[1,0]
	v_pk_mul_f32 v[16:17], v[16:17], s[98:99] op_sel_hi:[1,0]
	v_pk_mul_f32 v[14:15], v[14:15], s[98:99] op_sel_hi:[1,0]
	v_pk_mul_f32 v[12:13], v[12:13], s[98:99] op_sel_hi:[1,0]
	v_exp_f32_e32 v20, v20
	v_exp_f32_e32 v21, v21
	v_exp_f32_e32 v16, v16
	v_exp_f32_e32 v17, v17
	v_exp_f32_e32 v14, v14
	v_exp_f32_e32 v15, v15
	v_exp_f32_e32 v12, v12
	v_exp_f32_e32 v13, v13
	v_pk_add_f32 v[20:21], v[20:21], 1.0 op_sel_hi:[1,0]
	v_pk_add_f32 v[16:17], v[16:17], 1.0 op_sel_hi:[1,0]
	v_pk_add_f32 v[14:15], v[14:15], 1.0 op_sel_hi:[1,0]
	v_pk_add_f32 v[12:13], v[12:13], 1.0 op_sel_hi:[1,0]
	v_rcp_f32_e32 v20, v20
	v_rcp_f32_e32 v21, v21
	v_rcp_f32_e32 v16, v16
	v_rcp_f32_e32 v17, v17
	v_rcp_f32_e32 v14, v14
	v_rcp_f32_e32 v15, v15
	v_rcp_f32_e32 v12, v12
	v_rcp_f32_e32 v13, v13
	v_pk_mul_f32 v[20:21], v[20:21], s[32:33] op_sel_hi:[1,0]
	v_pk_mul_f32 v[16:17], v[16:17], s[32:33] op_sel_hi:[1,0]
	v_pk_mul_f32 v[14:15], v[14:15], s[32:33] op_sel_hi:[1,0]
	v_pk_mul_f32 v[12:13], v[12:13], s[32:33] op_sel_hi:[1,0]
	v_max_f32_e32 v20, 1.0, v20
	v_max_f32_e32 v21, 1.0, v21
	v_max_f32_e32 v16, 1.0, v16
	v_max_f32_e32 v17, 1.0, v17
	v_max_f32_e32 v14, 1.0, v14
	v_max_f32_e32 v15, 1.0, v15
	v_max_f32_e32 v12, 1.0, v12
	v_max_f32_e32 v13, 1.0, v13
	v_rndne_f32_e32 v20, v20
	v_rndne_f32_e32 v21, v21
	v_rndne_f32_e32 v16, v16
	v_rndne_f32_e32 v17, v17
	v_rndne_f32_e32 v14, v14
	v_rndne_f32_e32 v15, v15
	v_rndne_f32_e32 v12, v12
	v_rndne_f32_e32 v13, v13
	v_cvt_pk_u8_f32 v10, v20, 0, 0
	v_cvt_pk_u8_f32 v10, v21, 1, v10
	v_cvt_pk_u8_f32 v11, v14, 0, 0
	v_cvt_pk_u8_f32 v11, v15, 1, v11
	v_cvt_pk_u8_f32 v10, v16, 2, v10
	v_cvt_pk_u8_f32 v10, v17, 3, v10
	v_cvt_pk_u8_f32 v11, v12, 2, v11
	v_cvt_pk_u8_f32 v11, v13, 3, v11
	v_mov_b64_e32 v[24:25], s[30:31]
	v_mad_i64_i32 v[24:25], s[0:1], v22, s55, v[24:25]
	v_lshl_add_u64 v[24:25], v[24:25], 0, v[140:141]
	s_mov_b64 s[0:1], 0
	v_mov_b32_e32 v246, v10
	v_mov_b32_e32 v247, v11

.LBB0_761:
	v_mov_b32_e32 v19, v18
	v_mov_b32_e32 v12, v18
	v_mov_b32_e32 v13, v18
	v_pk_mul_f32 v[8:9], v[8:9], v[12:13]
	v_pk_mul_f32 v[6:7], v[6:7], v[18:19]
	v_pk_mul_f32 v[4:5], v[4:5], v[12:13]
	v_pk_mul_f32 v[2:3], v[2:3], v[18:19]
	s_and_b64 vcc, exec, s[42:43]
	s_mov_b64 s[0:1], -1
	s_cbranch_vccnz .LBB0_764
	s_mov_b32 s98, 0xbfb8aa3b
	s_mov_b32 s32, 0x437f0000
	v_pk_mul_f32 v[6:7], v[6:7], s[98:99] op_sel_hi:[1,0]
	v_pk_mul_f32 v[8:9], v[8:9], s[98:99] op_sel_hi:[1,0]
	v_pk_mul_f32 v[2:3], v[2:3], s[98:99] op_sel_hi:[1,0]
	v_pk_mul_f32 v[4:5], v[4:5], s[98:99] op_sel_hi:[1,0]
	v_exp_f32_e32 v6, v6
	v_exp_f32_e32 v7, v7
	v_exp_f32_e32 v8, v8
	v_exp_f32_e32 v9, v9
	v_exp_f32_e32 v2, v2
	v_exp_f32_e32 v3, v3
	v_exp_f32_e32 v4, v4
	v_exp_f32_e32 v5, v5
	v_pk_add_f32 v[6:7], v[6:7], 1.0 op_sel_hi:[1,0]
	v_pk_add_f32 v[8:9], v[8:9], 1.0 op_sel_hi:[1,0]
	v_pk_add_f32 v[2:3], v[2:3], 1.0 op_sel_hi:[1,0]
	v_pk_add_f32 v[4:5], v[4:5], 1.0 op_sel_hi:[1,0]
	v_rcp_f32_e32 v6, v6
	v_rcp_f32_e32 v7, v7
	v_rcp_f32_e32 v8, v8
	v_rcp_f32_e32 v9, v9
	v_rcp_f32_e32 v2, v2
	v_rcp_f32_e32 v3, v3
	v_rcp_f32_e32 v4, v4
	v_rcp_f32_e32 v5, v5
	v_pk_mul_f32 v[6:7], v[6:7], s[32:33] op_sel_hi:[1,0]
	v_pk_mul_f32 v[8:9], v[8:9], s[32:33] op_sel_hi:[1,0]
	v_pk_mul_f32 v[2:3], v[2:3], s[32:33] op_sel_hi:[1,0]
	v_pk_mul_f32 v[4:5], v[4:5], s[32:33] op_sel_hi:[1,0]
	v_max_f32_e32 v6, 1.0, v6
	v_max_f32_e32 v7, 1.0, v7
	v_max_f32_e32 v8, 1.0, v8
	v_max_f32_e32 v9, 1.0, v9
	v_max_f32_e32 v2, 1.0, v2
	v_max_f32_e32 v3, 1.0, v3
	v_max_f32_e32 v4, 1.0, v4
	v_max_f32_e32 v5, 1.0, v5
	v_rndne_f32_e32 v6, v6
	v_rndne_f32_e32 v7, v7
	v_rndne_f32_e32 v8, v8
	v_rndne_f32_e32 v9, v9
	v_rndne_f32_e32 v2, v2
	v_rndne_f32_e32 v3, v3
	v_rndne_f32_e32 v4, v4
	v_rndne_f32_e32 v5, v5
	v_cvt_pk_u8_f32 v12, v6, 0, 0
	v_cvt_pk_u8_f32 v12, v7, 1, v12
	v_cvt_pk_u8_f32 v13, v2, 0, 0
	v_cvt_pk_u8_f32 v13, v3, 1, v13
	v_cvt_pk_u8_f32 v12, v8, 2, v12
	v_cvt_pk_u8_f32 v12, v9, 3, v12
	v_cvt_pk_u8_f32 v13, v4, 2, v13
	v_cvt_pk_u8_f32 v13, v5, 3, v13
	v_mov_b64_e32 v[14:15], s[30:31]
	v_mad_i64_i32 v[14:15], s[0:1], v22, s55, v[14:15]
	v_lshl_add_u64 v[14:15], v[14:15], 0, v[140:141]
	v_mov_b32_e32 v244, v12
	v_mov_b32_e32 v245, v13
	v_mov_b32_e32 v250, v176
	v_mov_b32_e32 v251, 0
	v_lshl_add_u64 v[14:15], v[14:15], 0, v[250:251]
	global_store_dwordx4 v[14:15], v[244:247], off
	s_cbranch_execz .LBB0_765
